# diff-attn loop: deferred-max fast path (alpha/rescale math only when a row exceeds the threshold), saddr K/V loads, fewer max ops
# baseline (speedup 1.0000x reference)
; #define SBAR() __builtin_amdgcn_sched_barrier(0)
; __device__ __forceinline__ int v_rd_base(int lane) { return ((lane & 3) << 3) | (((lane >> 2) & 3) << 6) | (((lane >> 4) & 1) << 5) | (((lane >> 5) & 1) << 8); }
; __device__ __forceinline__ void partialSM(f32x16& p0, f32x16& p1, float& m_reg, float& mn, float& alpha) {
;     float pmax = p0[0]; for (int r = 1; r < 16; ++r) pmax = fmaxf(pmax, p0[r]); for (int r = 0; r < 16; ++r) pmax = fmaxf(pmax, p1[r]);
;     { auto rr = __builtin_amdgcn_permlane32_swap(__float_as_uint(pmax), __float_as_uint(pmax), false, false);
;       pmax = fmaxf(__uint_as_float(rr[0]), __uint_as_float(rr[1])); }
;     constexpr float C2 = 1.4426950408889634f * SCALE;
;     if (__builtin_expect(__all((pmax - m_reg) * SCALE <= THR), 1)) { mn = m_reg; alpha = 1.f; }
;     else { mn = fmaxf(m_reg, pmax); alpha = __builtin_amdgcn_exp2f((m_reg - mn) * C2); m_reg = mn; }
;     const float mnL = -mn * C2;
;     for (int r = 0; r < 16; ++r) p0[r] = fmaf(p0[r], C2, mnL); for (int r = 0; r < 16; ++r) p1[r] = fmaf(p1[r], C2, mnL);
;     for (int r = 0; r < 16; ++r) p0[r] = __builtin_amdgcn_exp2f(p0[r]);
; }
; template <class TIn, class TOut>
; __device__ __forceinline__ void causal_swa_block(const BlockRef<TIn, TOut>& cur, const BlockRef<TIn, TOut>& nxt, int skv, int W, char* lds, Seam<TIn>& S) {
;     ...
;     float m_reg = -1e30f, l_reg = 0; f32x16 o[4] = {};
;     const int sr = tid >> 4, sc = (tid & 15) * 8, vst0 = v_st(sr, sc), vst1 = v_st(32 + sr, sc), kws = KSWZ(sr, sc * 2);
;     const int vb0 = (int)(uintptr_t)V_lds + v_rd_base(lane);
;     const TIn* Kh = cur.K; const TIn* Vh = cur.V;
;     ...
;     constexpr int NQL = F32 ? 16 : 8;
;     constexpr bool SK = WSKIP && !F32;
;     ...
;     f32x16 pA0, pA1, pB0, pB1; float mnA, mnB, alA, alB; bf16x8 pa0, pa1, pa2, pa3;
;     if constexpr (F32) { VMW(); SWRITE_VF(0); SBAR(); } else { SWRITE_HV(0); SBAR(); }
;     if (NT > 1) { if constexpr (F32) SLOAD_F((const float*)Kh, KBASE(1)); else SLOAD_H(Kh, Vh, KBASE(1)); }
;     SBAR(); qkt<0, SK>(pA0, pA1, K_lds, r32, hi, S.qr, ACT(0));
;     if constexpr (F32) { if (NT > 1) { VMW(); SWRITE_KF(1); SBAR(); SLOAD_F((const float*)Vh, KBASE(1)); } }
;     MASKT(pA0, pA1, 0); partialSM(pA0, pA1, m_reg, mnA, alA);
;     if (NT > 1) { VMW(); if constexpr (F32) { SWRITE_VF(1); SBAR(); if (NT > 2) SLOAD_F((const float*)Kh, KBASE(2)); } else SWRITE_H(1); }
;     __syncthreads();
.LBB0_1128:
	s_nop 8
	v_max_f32_e32 v50, v19, v19
	v_max_f32_e32 v51, v18, v18
	v_max_f32_e32 v50, v51, v50
	v_max3_f32 v50, v50, v20, v21
	v_max3_f32 v50, v50, v22, v23
	v_max3_f32 v50, v50, v24, v25
	v_max3_f32 v50, v50, v26, v27
	v_max3_f32 v50, v50, v28, v29
	v_max3_f32 v50, v50, v30, v31
	v_max3_f32 v50, v50, v32, v33
	v_max3_f32 v50, v50, v2, v3
	v_max3_f32 v50, v50, v4, v5
	v_max3_f32 v50, v50, v6, v7
	v_max3_f32 v50, v50, v8, v9
	v_max3_f32 v50, v50, v10, v11
	v_max3_f32 v50, v50, v12, v13
	v_max3_f32 v50, v50, v14, v15
	v_max3_f32 v50, v50, v16, v17
	v_mov_b32_e32 v51, v50
	s_nop 1
	v_permlane32_swap_b32_e32 v50, v51
	v_max_f32_e32 v51, v51, v51
	v_max_f32_e32 v50, v50, v50
	v_max_f32_e32 v50, v50, v51
	s_and_b32 s4, s4, 0x3fffffc0
	v_add_f32_e32 v51, 0x7149f2ca, v50
	s_lshl_b32 s4, s4, 2
	v_mul_f32_e32 v51, 0x3db504f3, v51
	v_max_f32_e32 v50, 0xf149f2ca, v50
	s_add_i32 s14, s80, 0xff
	s_add_i32 s4, s4, 0
	v_cmp_ge_f32_e32 vcc, s86, v51
	v_sub_f32_e32 v51, 0xf149f2ca, v50
	s_lshr_b32 s24, s14, 6
	s_add_i32 s4, s4, 0x10000
	s_add_i32 s15, s13, 0xffffc01f
	v_mul_f32_e32 v51, 0x3e0293ee, v51
	v_exp_f32_e32 v51, v51
	s_cmp_eq_u64 vcc, exec
	s_cselect_b64 vcc, -1, 0
	v_cndmask_b32_e32 v178, v50, v216, vcc
	v_mul_f32_e32 v50, 0xbe0293ee, v178
	v_cndmask_b32_e64 v197, v51, 1.0, vcc
	v_mov_b32_e32 v51, v50
	v_fmamk_f32 v18, v18, 0x3e0293ee, v50
	v_fmamk_f32 v19, v19, 0x3e0293ee, v50
	v_fmamk_f32 v20, v20, 0x3e0293ee, v50
	v_fmamk_f32 v21, v21, 0x3e0293ee, v50
	v_fmamk_f32 v22, v22, 0x3e0293ee, v50
	v_fmamk_f32 v23, v23, 0x3e0293ee, v50
	v_fmamk_f32 v24, v24, 0x3e0293ee, v50
	v_fmamk_f32 v25, v25, 0x3e0293ee, v50
	v_fmamk_f32 v26, v26, 0x3e0293ee, v50
	v_fmamk_f32 v27, v27, 0x3e0293ee, v50
	v_fmamk_f32 v28, v28, 0x3e0293ee, v50
	v_fmamk_f32 v29, v29, 0x3e0293ee, v50
	v_fmamk_f32 v30, v30, 0x3e0293ee, v50
	v_fmamk_f32 v31, v31, 0x3e0293ee, v50
	v_fmamk_f32 v32, v32, 0x3e0293ee, v50
	v_fmac_f32_e32 v51, 0x3e0293ee, v33
	v_exp_f32_e32 v170, v18
	v_exp_f32_e32 v171, v19
	v_exp_f32_e32 v172, v20
	v_exp_f32_e32 v173, v21
	v_exp_f32_e32 v174, v22
	v_exp_f32_e32 v176, v23
	v_exp_f32_e32 v175, v24
	v_exp_f32_e32 v177, v25
	v_exp_f32_e32 v162, v26
	v_exp_f32_e32 v163, v27
	v_exp_f32_e32 v164, v28
	v_exp_f32_e32 v166, v29
	v_exp_f32_e32 v165, v30
	v_exp_f32_e32 v167, v31
	v_exp_f32_e32 v168, v32
	v_exp_f32_e32 v169, v51
	s_waitcnt vmcnt(0)
	s_waitcnt vmcnt(3)
	ds_write_b128 v209, v[34:37] offset:16384
	s_waitcnt vmcnt(1)
	ds_write_b128 v210, v[46:49] offset:16384
	ds_write_b128 v217, v[38:41] offset:49152
	s_waitcnt vmcnt(0)
	ds_write_b128 v217, v[42:45] offset:57344
	v_mov_b32_e32 v34, v195
	v_mov_b32_e32 v35, v195
	v_mov_b32_e32 v48, v195
	v_mov_b32_e32 v49, v195
	v_pk_fma_f32 v[118:119], v[16:17], s[50:51], v[50:51] op_sel_hi:[1,0,0]
	v_pk_fma_f32 v[122:123], v[14:15], s[50:51], v[50:51] op_sel_hi:[1,0,0]
	v_pk_fma_f32 v[128:129], v[12:13], s[50:51], v[50:51] op_sel_hi:[1,0,0]
	v_pk_fma_f32 v[114:115], v[10:11], s[50:51], v[50:51] op_sel_hi:[1,0,0]
	v_pk_fma_f32 v[116:117], v[8:9], s[50:51], v[50:51] op_sel_hi:[1,0,0]
	v_pk_fma_f32 v[120:121], v[6:7], s[50:51], v[50:51] op_sel_hi:[1,0,0]
	v_pk_fma_f32 v[124:125], v[4:5], s[50:51], v[50:51] op_sel_hi:[1,0,0]
	v_pk_fma_f32 v[126:127], v[2:3], s[50:51], v[50:51] op_sel_hi:[1,0,0]
	v_mov_b32_e32 v36, v195
	v_mov_b32_e32 v37, v195
	v_mov_b32_e32 v38, v195
	v_mov_b32_e32 v39, v195
	v_mov_b32_e32 v40, v195
	v_mov_b32_e32 v41, v195
	v_mov_b32_e32 v42, v195
	v_mov_b32_e32 v43, v195
	v_mov_b32_e32 v44, v195
	v_mov_b32_e32 v45, v195
	v_mov_b32_e32 v46, v195
	v_mov_b32_e32 v47, v195
	v_mov_b64_e32 v[64:65], v[48:49]
	v_mov_b64_e32 v[18:19], v[34:35]
	v_mov_b64_e32 v[2:3], v[34:35]
	s_mov_b32 s25, 2
	v_lshl_add_u32 v219, v199, 2, s4
	v_lshl_add_u32 v218, v200, 2, s4
	v_add_u32_e32 v222, s12, v201
	v_mov_b32_e32 v221, 0
	s_movk_i32 s26, 0xbf
	v_mov_b32_e32 v194, v203
	v_mov_b64_e32 v[62:63], v[46:47]
	v_mov_b64_e32 v[60:61], v[44:45]
	v_mov_b64_e32 v[58:59], v[42:43]
	v_mov_b64_e32 v[56:57], v[40:41]
	v_mov_b64_e32 v[54:55], v[38:39]
	v_mov_b64_e32 v[52:53], v[36:37]
	v_mov_b64_e32 v[50:51], v[34:35]
	v_mov_b64_e32 v[20:21], v[36:37]
	v_mov_b64_e32 v[22:23], v[38:39]
	v_mov_b64_e32 v[24:25], v[40:41]
	v_mov_b64_e32 v[26:27], v[42:43]
	v_mov_b64_e32 v[28:29], v[44:45]
	v_mov_b64_e32 v[30:31], v[46:47]
	v_mov_b64_e32 v[32:33], v[48:49]
	v_mov_b64_e32 v[4:5], v[36:37]
	v_mov_b64_e32 v[6:7], v[38:39]
	v_mov_b64_e32 v[8:9], v[40:41]
	v_mov_b64_e32 v[10:11], v[42:43]
	v_mov_b64_e32 v[12:13], v[44:45]
	v_mov_b64_e32 v[14:15], v[46:47]
	v_mov_b64_e32 v[16:17], v[48:49]
	s_waitcnt lgkmcnt(0)
	s_barrier
	v_lshlrev_b32_e32 v255, 1, v194
	v_mov_b32_e32 v252, v178
	v_mul_f32_e32 v253, 0xbe0293ee, v178
; template <int KB, bool SK>
; __device__ __forceinline__ void qkt(f32x16& p0, f32x16& p1, const char* K_lds, int r32, int hi, const bf16x8* qr, bool act) {
;     if (SK && !act) { const float NEG = -__builtin_inff();
; #pragma unroll
;         for (int r = 0; r < 16; ++r) { p0[r] = NEG; p1[r] = NEG; } return; }
;     p0 = f32x16{}; p1 = f32x16{};
;     const char* kb[4];
; #pragma unroll
;     for (int dd = 0; dd < 4; ++dd) kb[dd] = K_lds + KB * SHM_K + KSWZ(r32, (dd * 16 + hi * 8) * 2);
; #pragma unroll
;     for (int d0 = 0; d0 < 8; ++d0) { const char* a = kb[d0 & 3] + (d0 >> 2) * 128;
;         bf16x8 b0 = *reinterpret_cast<const bf16x8*>(a);
;         bf16x8 b1 = *reinterpret_cast<const bf16x8*>(a + 32 * 256);
;         const bf16x8 qf = qr[d0];
;         p0 = __builtin_amdgcn_mfma_f32_32x32x16_bf16(b0, qf, p0, 0, 0, 0);
;         p1 = __builtin_amdgcn_mfma_f32_32x32x16_bf16(b1, qf, p1, 0, 0, 0); }
; }
.LBB0_1129:
	ds_read_b128 v[180:183], v211 offset:49152
	ds_read_b128 v[184:187], v211 offset:57344
	ds_read_b128 v[188:191], v212 offset:49152
	ds_read_b128 v[228:231], v212 offset:57344
	ds_read_b128 v[232:235], v213 offset:49152
	ds_read_b128 v[236:239], v213 offset:57344
	ds_read_b128 v[240:243], v214 offset:49152
	ds_read_b128 v[244:247], v214 offset:57344
	v_exp_f32_e32 v126, v126
	v_exp_f32_e32 v127, v127
	v_exp_f32_e32 v124, v124
	v_exp_f32_e32 v125, v125
	v_exp_f32_e32 v120, v120
	v_exp_f32_e32 v121, v121
	v_exp_f32_e32 v116, v116
	v_exp_f32_e32 v117, v117
	v_exp_f32_e32 v114, v114
	v_exp_f32_e32 v115, v115
	v_exp_f32_e32 v128, v128
	v_exp_f32_e32 v129, v129
	v_exp_f32_e32 v122, v122
	v_exp_f32_e32 v123, v123
	v_exp_f32_e32 v118, v118
	v_exp_f32_e32 v119, v119
	s_add_i32 s4, s26, 0xffffff81
	s_sub_i32 s5, s26, 64
	s_waitcnt lgkmcnt(7)
	v_mfma_f32_32x32x16_bf16 v[86:101], v[180:183], v[158:161], 0
	ds_read_b128 v[180:183], v211 offset:49280
	v_add_f32_e32 v179, 0, v170
	v_add_f32_e32 v179, v171, v179
	v_add_f32_e32 v179, v172, v179
	v_add_f32_e32 v179, v173, v179
	s_waitcnt lgkmcnt(7)
	v_mfma_f32_32x32x16_bf16 v[70:85], v[184:187], v[158:161], 0
	ds_read_b128 v[184:187], v211 offset:57472
	v_add_f32_e32 v179, v174, v179
	v_add_f32_e32 v179, v176, v179
	v_add_f32_e32 v179, v175, v179
	v_add_f32_e32 v179, v177, v179
	s_waitcnt lgkmcnt(7)
	v_mfma_f32_32x32x16_bf16 v[86:101], v[188:191], v[154:157], v[86:101]
	ds_read_b128 v[188:191], v212 offset:49280
	v_add_f32_e32 v179, v162, v179
	v_add_f32_e32 v179, v163, v179
	v_add_f32_e32 v110, v164, v179
	v_add_f32_e32 v110, v166, v110
	s_waitcnt lgkmcnt(7)
	v_mfma_f32_32x32x16_bf16 v[70:85], v[228:231], v[154:157], v[70:85]
	ds_read_b128 v[228:231], v212 offset:57472
	v_add_f32_e32 v110, v165, v110
	v_add_f32_e32 v110, v167, v110
	v_add_f32_e32 v110, v168, v110
	v_add_f32_e32 v110, v169, v110
	s_waitcnt lgkmcnt(7)
	v_mfma_f32_32x32x16_bf16 v[86:101], v[232:235], v[150:153], v[86:101]
	ds_read_b128 v[232:235], v213 offset:49280
	v_add_f32_e32 v110, v126, v110
	v_add_f32_e32 v102, v127, v110
	v_add_f32_e32 v102, v124, v102
	v_add_f32_e32 v102, v125, v102
	s_waitcnt lgkmcnt(7)
	v_mfma_f32_32x32x16_bf16 v[70:85], v[236:239], v[150:153], v[70:85]
	ds_read_b128 v[236:239], v213 offset:57472
	v_add_f32_e32 v102, v120, v102
	v_add_f32_e32 v102, v121, v102
	v_add_f32_e32 v102, v116, v102
	v_add_f32_e32 v102, v117, v102
	s_waitcnt lgkmcnt(7)
	v_mfma_f32_32x32x16_bf16 v[86:101], v[240:243], v[134:137], v[86:101]
	ds_read_b128 v[240:243], v214 offset:49280
	v_add_f32_e32 v102, v114, v102
	v_add_f32_e32 v102, v115, v102
	v_add_f32_e32 v102, v128, v102
	v_add_f32_e32 v102, v129, v102
	s_waitcnt lgkmcnt(7)
	v_mfma_f32_32x32x16_bf16 v[70:85], v[244:247], v[134:137], v[70:85]
	ds_read_b128 v[244:247], v214 offset:57472
	v_add_f32_e32 v102, v122, v102
	v_add_f32_e32 v102, v123, v102
	v_add_f32_e32 v102, v118, v102
	v_add_f32_e32 v223, v119, v102
	s_waitcnt lgkmcnt(7)
	v_mfma_f32_32x32x16_bf16 v[86:101], v[180:183], v[138:141], v[86:101]
	v_mov_b32_e32 v224, v223
	s_nop 1
	v_permlane32_swap_b32_e32 v223, v224
	v_cvt_pk_bf16_f32 v102, v170, v171
	v_cvt_pk_bf16_f32 v103, v172, v173
	s_waitcnt lgkmcnt(6)
	v_mfma_f32_32x32x16_bf16 v[70:85], v[184:187], v[138:141], v[70:85]
	v_cvt_pk_bf16_f32 v104, v174, v176
	v_cvt_pk_bf16_f32 v105, v175, v177
	v_cvt_pk_bf16_f32 v66, v162, v163
	v_cvt_pk_bf16_f32 v67, v164, v166
	s_waitcnt lgkmcnt(5)
	v_mfma_f32_32x32x16_bf16 v[86:101], v[188:191], v[142:145], v[86:101]
	v_cvt_pk_bf16_f32 v68, v165, v167
	v_cvt_pk_bf16_f32 v69, v168, v169
	v_cvt_pk_bf16_f32 v106, v126, v127
	s_waitcnt lgkmcnt(4)
	v_mfma_f32_32x32x16_bf16 v[70:85], v[228:231], v[142:145], v[70:85]
	v_cvt_pk_bf16_f32 v107, v124, v125
	v_cvt_pk_bf16_f32 v108, v120, v121
	v_cvt_pk_bf16_f32 v109, v116, v117
	s_waitcnt lgkmcnt(3)
	v_mfma_f32_32x32x16_bf16 v[86:101], v[232:235], v[146:149], v[86:101]
	v_cvt_pk_bf16_f32 v110, v114, v115
	v_cvt_pk_bf16_f32 v111, v128, v129
	v_cvt_pk_bf16_f32 v112, v122, v123
	s_waitcnt lgkmcnt(2)
	v_mfma_f32_32x32x16_bf16 v[70:85], v[236:239], v[146:149], v[70:85]
	v_cvt_pk_bf16_f32 v113, v118, v119
	s_nop 1
	v_permlane32_swap_b32_e32 v102, v104
	v_permlane32_swap_b32_e32 v103, v105
	s_waitcnt lgkmcnt(1)
	v_mfma_f32_32x32x16_bf16 v[86:101], v[240:243], v[130:133], v[86:101]
	v_permlane32_swap_b32_e32 v66, v68
	v_permlane32_swap_b32_e32 v67, v69
	v_permlane32_swap_b32_e32 v106, v108
	s_waitcnt lgkmcnt(0)
	v_mfma_f32_32x32x16_bf16 v[70:85], v[244:247], v[130:133], v[70:85]
	v_permlane32_swap_b32_e32 v107, v109
	v_permlane32_swap_b32_e32 v110, v112
	v_permlane32_swap_b32_e32 v111, v113
	v_add_u32_e32 v114, 0x2000, v255
	global_load_dwordx4 v[162:165], v255, s[42:43]
	global_load_dwordx4 v[166:169], v114, s[42:43]
	global_load_dwordx4 v[170:173], v255, s[22:23]
	global_load_dwordx4 v[174:177], v114, s[22:23]
	s_cmp_le_i32 s5, s13
	s_cselect_b64 s[52:53], -1, 0
	s_cmp_gt_i32 s4, s15
	s_cselect_b64 s[4:5], -1, 0
	s_and_b64 s[4:5], s[52:53], s[4:5]
	s_and_b64 vcc, exec, s[4:5]
	ds_read_b64_tr_b16 v[114:115], v202 offset:0x0
	ds_read_b64_tr_b16 v[116:117], v202 offset:0x800
	ds_read_b64_tr_b16 v[118:119], v202 offset:0x1000
	ds_read_b64_tr_b16 v[120:121], v202 offset:0x1800
	ds_read_b64_tr_b16 v[122:123], v202 offset:0x2000
	ds_read_b64_tr_b16 v[124:125], v202 offset:0x2800
	ds_read_b64_tr_b16 v[126:127], v202 offset:0x3000
	ds_read_b64_tr_b16 v[128:129], v202 offset:0x3800
	s_cbranch_vccnz .Lh1_nomask
; __device__ __forceinline__ void mask_tile(f32x16& p0, f32x16& p1, int dq, unsigned W) {
;     const float NEG = -__builtin_inff();
; #pragma unroll
;     for (int r = 0; r < 16; ++r) {
;         const int c = (r & 3) + 8 * (r >> 2);
;         if ((unsigned)(dq - c) >= W) p0[r] = NEG;
;         if ((unsigned)(dq - c - 32) >= W) p1[r] = NEG;
;     }
; }
; __device__ __forceinline__ void partialSM(f32x16& p0, f32x16& p1, float& m_reg, float& mn, float& alpha) {
;     float pmax = p0[0]; for (int r = 1; r < 16; ++r) pmax = fmaxf(pmax, p0[r]); for (int r = 0; r < 16; ++r) pmax = fmaxf(pmax, p1[r]);
;     { auto rr = __builtin_amdgcn_permlane32_swap(__float_as_uint(pmax), __float_as_uint(pmax), false, false);
;       pmax = fmaxf(__uint_as_float(rr[0]), __uint_as_float(rr[1])); }
;     constexpr float C2 = 1.4426950408889634f * SCALE;
;     if (__builtin_expect(__all((pmax - m_reg) * SCALE <= THR), 1)) { mn = m_reg; alpha = 1.f; }
;     else { mn = fmaxf(m_reg, pmax); alpha = __builtin_amdgcn_exp2f((m_reg - mn) * C2); m_reg = mn; }
;     const float mnL = -mn * C2;
;     for (int r = 0; r < 16; ++r) p0[r] = fmaf(p0[r], C2, mnL); for (int r = 0; r < 16; ++r) p1[r] = fmaf(p1[r], C2, mnL);
;     for (int r = 0; r < 16; ++r) p0[r] = __builtin_amdgcn_exp2f(p0[r]);
; }
; template <int VB, bool SK>
; __device__ __forceinline__ void pv_tile(f32x16* o, int vb0, bf16x8 pa0, bf16x8 pa1, bf16x8 pa2, bf16x8 pa3, bool act) {
;     if (SK && !act) return;
;     ...
;     PV_D0(0); PV_D0(1); PV_D0(2); PV_D0(3);
	v_add_u32_e32 v226, s80, v222
	v_subrev_u32_e32 v240, 64, v226
	v_cmp_gt_u32_e32 vcc, s85, v240
	v_add_u32_e32 v240, 0xffffffa0, v226
	s_nop 0
	v_cndmask_b32_e32 v86, v215, v86, vcc
	v_cmp_gt_u32_e32 vcc, s85, v240
	v_add_u32_e32 v240, 0xffffffbf, v226
	s_nop 0
	v_cndmask_b32_e32 v70, v215, v70, vcc
	v_cmp_gt_u32_e32 vcc, s85, v240
	v_add_u32_e32 v240, 0xffffff9f, v226
	s_nop 0
	v_cndmask_b32_e32 v87, v215, v87, vcc
	v_cmp_gt_u32_e32 vcc, s85, v240
	v_add_u32_e32 v240, 0xffffffbe, v226
	s_nop 0
	v_cndmask_b32_e32 v71, v215, v71, vcc
	v_cmp_gt_u32_e32 vcc, s85, v240
	v_add_u32_e32 v240, 0xffffff9e, v226
	s_nop 0
	v_cndmask_b32_e32 v88, v215, v88, vcc
	v_cmp_gt_u32_e32 vcc, s85, v240
	v_add_u32_e32 v240, 0xffffffbd, v226
	s_nop 0
	v_cndmask_b32_e32 v72, v215, v72, vcc
	v_cmp_gt_u32_e32 vcc, s85, v240
	v_add_u32_e32 v240, 0xffffff9d, v226
	s_nop 0
	v_cndmask_b32_e32 v89, v215, v89, vcc
	v_cmp_gt_u32_e32 vcc, s85, v240
	v_add_u32_e32 v240, 0xffffffb8, v226
	s_nop 0
	v_cndmask_b32_e32 v73, v215, v73, vcc
	v_cmp_gt_u32_e32 vcc, s85, v240
	v_add_u32_e32 v240, 0xffffff98, v226
	s_nop 0
	v_cndmask_b32_e32 v90, v215, v90, vcc
	v_cmp_gt_u32_e32 vcc, s85, v240
	v_add_u32_e32 v240, 0xffffffb7, v226
	s_nop 0
	v_cndmask_b32_e32 v74, v215, v74, vcc
	v_cmp_gt_u32_e32 vcc, s85, v240
	v_add_u32_e32 v240, 0xffffff97, v226
	s_nop 0
	v_cndmask_b32_e32 v91, v215, v91, vcc
	v_cmp_gt_u32_e32 vcc, s85, v240
	v_add_u32_e32 v240, 0xffffffb6, v226
	s_nop 0
	v_cndmask_b32_e32 v75, v215, v75, vcc
	v_cmp_gt_u32_e32 vcc, s85, v240
	v_add_u32_e32 v240, 0xffffff96, v226
	s_nop 0
	v_cndmask_b32_e32 v92, v215, v92, vcc
	v_cmp_gt_u32_e32 vcc, s85, v240
	v_add_u32_e32 v240, 0xffffffb5, v226
	s_nop 0
	v_cndmask_b32_e32 v76, v215, v76, vcc
	v_cmp_gt_u32_e32 vcc, s85, v240
	v_add_u32_e32 v240, 0xffffff95, v226
	s_nop 0
	v_cndmask_b32_e32 v93, v215, v93, vcc
	v_cmp_gt_u32_e32 vcc, s85, v240
	v_add_u32_e32 v240, 0xffffffb0, v226
	s_nop 0
	v_cndmask_b32_e32 v77, v215, v77, vcc
	v_cmp_gt_u32_e32 vcc, s85, v240
	v_add_u32_e32 v240, 0xffffff90, v226
	s_nop 0
	v_cndmask_b32_e32 v94, v215, v94, vcc
	v_cmp_gt_u32_e32 vcc, s85, v240
	v_add_u32_e32 v240, 0xffffffaf, v226
	s_nop 0
	v_cndmask_b32_e32 v78, v215, v78, vcc
	v_cmp_gt_u32_e32 vcc, s85, v240
	v_add_u32_e32 v240, 0xffffff8f, v226
	s_nop 0
	v_cndmask_b32_e32 v95, v215, v95, vcc
	v_cmp_gt_u32_e32 vcc, s85, v240
	v_add_u32_e32 v240, 0xffffffae, v226
	s_nop 0
	v_cndmask_b32_e32 v79, v215, v79, vcc
	v_cmp_gt_u32_e32 vcc, s85, v240
	v_add_u32_e32 v240, 0xffffff8e, v226
	s_nop 0
	v_cndmask_b32_e32 v96, v215, v96, vcc
	v_cmp_gt_u32_e32 vcc, s85, v240
	v_add_u32_e32 v240, 0xffffffad, v226
	s_nop 0
	v_cndmask_b32_e32 v80, v215, v80, vcc
	v_cmp_gt_u32_e32 vcc, s85, v240
	v_add_u32_e32 v240, 0xffffff8d, v226
	s_nop 0
	v_cndmask_b32_e32 v97, v215, v97, vcc
	v_cmp_gt_u32_e32 vcc, s85, v240
	v_add_u32_e32 v240, 0xffffffa8, v226
	s_nop 0
	v_cndmask_b32_e32 v81, v215, v81, vcc
	v_cmp_gt_u32_e32 vcc, s85, v240
	v_add_u32_e32 v240, 0xffffff88, v226
	s_nop 0
	v_cndmask_b32_e32 v98, v215, v98, vcc
	v_cmp_gt_u32_e32 vcc, s85, v240
	v_add_u32_e32 v240, 0xffffffa7, v226
	s_nop 0
	v_cndmask_b32_e32 v82, v215, v82, vcc
	v_cmp_gt_u32_e32 vcc, s85, v240
	v_add_u32_e32 v240, 0xffffff87, v226
	s_nop 0
	v_cndmask_b32_e32 v99, v215, v99, vcc
	v_cmp_gt_u32_e32 vcc, s85, v240
	v_add_u32_e32 v240, 0xffffffa6, v226
	s_nop 0
	v_cndmask_b32_e32 v83, v215, v83, vcc
	v_cmp_gt_u32_e32 vcc, s85, v240
	v_add_u32_e32 v240, 0xffffff86, v226
	s_nop 0
	v_cndmask_b32_e32 v100, v215, v100, vcc
	v_cmp_gt_u32_e32 vcc, s85, v240
	v_add_u32_e32 v240, 0xffffffa5, v226
	s_nop 0
	v_cndmask_b32_e32 v84, v215, v84, vcc
	v_cmp_gt_u32_e32 vcc, s85, v240
	v_add_u32_e32 v240, 0xffffff85, v226
	s_nop 0
	v_cndmask_b32_e32 v101, v215, v101, vcc
	v_cmp_gt_u32_e32 vcc, s85, v240
	s_nop 1
	v_cndmask_b32_e32 v85, v215, v85, vcc
.Lh1_nomask:
	v_max_f32_e32 v240, v86, v87
	v_max3_f32 v240, v240, v88, v89
	v_max3_f32 v240, v240, v90, v91
	v_max3_f32 v240, v240, v92, v93
	v_max3_f32 v240, v240, v94, v95
	s_waitcnt lgkmcnt(6)
	v_mfma_f32_32x32x16_bf16 v[34:49], v[102:105], v[114:117], v[34:49]
	ds_read_b64_tr_b16 v[114:115], v202 offset:0x200
	ds_read_b64_tr_b16 v[116:117], v202 offset:0xa00
	v_max3_f32 v240, v240, v96, v97
	v_max3_f32 v240, v240, v98, v99
	v_max3_f32 v240, v240, v100, v101
	v_max3_f32 v240, v240, v70, v71
	s_waitcnt lgkmcnt(6)
	v_mfma_f32_32x32x16_bf16 v[34:49], v[66:69], v[118:121], v[34:49]
	ds_read_b64_tr_b16 v[118:119], v202 offset:0x1200
	ds_read_b64_tr_b16 v[120:121], v202 offset:0x1a00
	v_max3_f32 v240, v240, v72, v73
	v_max3_f32 v240, v240, v74, v75
	v_max3_f32 v240, v240, v76, v77
	v_max3_f32 v240, v240, v78, v79
	s_waitcnt lgkmcnt(6)
	v_mfma_f32_32x32x16_bf16 v[34:49], v[106:109], v[122:125], v[34:49]
	ds_read_b64_tr_b16 v[122:123], v202 offset:0x2200
	ds_read_b64_tr_b16 v[124:125], v202 offset:0x2a00
	v_max3_f32 v240, v240, v80, v81
	v_max3_f32 v240, v240, v82, v83
	v_max3_f32 v240, v240, v84, v85
	v_mov_b32_e32 v241, v240
	s_waitcnt lgkmcnt(6)
	v_mfma_f32_32x32x16_bf16 v[34:49], v[110:113], v[126:129], v[34:49]
	ds_read_b64_tr_b16 v[126:127], v202 offset:0x3200
	ds_read_b64_tr_b16 v[128:129], v202 offset:0x3a00
	s_nop 1
	v_permlane32_swap_b32_e32 v240, v241
	v_max_f32_e32 v240, v240, v241
	v_sub_f32_e32 v241, v240, v252
	v_mul_f32_e32 v241, 0x3db504f3, v241
	s_waitcnt lgkmcnt(6)
	v_mfma_f32_32x32x16_bf16 v[50:65], v[102:105], v[114:117], v[50:65]
	ds_read_b64_tr_b16 v[114:115], v202 offset:0x400
	ds_read_b64_tr_b16 v[116:117], v202 offset:0xc00
	v_cmp_ge_f32_e32 vcc, s86, v241
	s_cmp_eq_u64 vcc, exec
	s_cselect_b64 s[4:5], -1, 0
	v_mov_b32_e32 v225, 1.0
	s_cbranch_scc0 .Lh1_rare
; #define SBAR() __builtin_amdgcn_sched_barrier(0)
; #define VMW() asm volatile("s_waitcnt vmcnt(0)" ::: "memory")
; #define SLOAD_H(Kp, Vp, k0) do { S.st_v0 = load8<TIn>(ROW(Vp, k0, sr)); S.st_v1 = load8<TIn>(ROW(Vp, k0, 32 + sr));              \
;                          S.st_k0 = load8<TIn>(ROW(Kp, k0, sr)); S.st_k1 = load8<TIn>(ROW(Kp, k0, 32 + sr)); } while (0)
; #define SWRITE_HV(bf) do { *(bf16x8*)(V_lds + (bf) * SHM_V + vst0) = S.st_v0; *(bf16x8*)(V_lds + (bf) * SHM_V + vst1) = S.st_v1; } while (0)
; #define SWRITE_H(bf) do { SWRITE_HV(bf); SWRITE_HK(bf); } while (0)
; #define SLOAD_F(p, k0) do { S.sf0 = *(const f32x4*)ROW(p, k0, sr); S.sf1 = *(const f32x4*)(ROW(p, k0, sr) + 4);                \
;                             S.sf2 = *(const f32x4*)ROW(p, k0, 32 + sr); S.sf3 = *(const f32x4*)(ROW(p, k0, 32 + sr) + 4); } while (0)
; #define SWRITE_KF(bf) do { *(bf16x8*)(K_lds + (bf) * SHM_K + kws) = pack8(S.sf0, S.sf1); *(bf16x8*)(K_lds + (bf) * SHM_K + kws + 32 * 256) = pack8(S.sf2, S.sf3); } while (0)
; #define SWRITE_VF(bf) do { *(bf16x8*)(V_lds + (bf) * SHM_V + vst0) = pack8(S.sf0, S.sf1); *(bf16x8*)(V_lds + (bf) * SHM_V + vst1) = pack8(S.sf2, S.sf3); } while (0)
; #define ACT(t) (KBASE(t) <= qlo + QBLK - 1 && KBASE(t) + KVBLK - 1 >= qlo - W + 1)
; template <class TIn, class TOut>
; __device__ __forceinline__ void causal_swa_block(const BlockRef<TIn, TOut>& cur, const BlockRef<TIn, TOut>& nxt, int skv, int W, char* lds, Seam<TIn>& S) {
;     ...
;     constexpr int NQL = F32 ? 16 : 8;
;     constexpr bool SK = WSKIP && !F32;
;     ...
;     f32x16 pA0, pA1, pB0, pB1; float mnA, mnB, alA, alB; bf16x8 pa0, pa1, pa2, pa3;
;     if constexpr (F32) { VMW(); SWRITE_VF(0); SBAR(); } else { SWRITE_HV(0); SBAR(); }
;     if (NT > 1) { if constexpr (F32) SLOAD_F((const float*)Kh, KBASE(1)); else SLOAD_H(Kh, Vh, KBASE(1)); }
;     SBAR(); qkt<0, SK>(pA0, pA1, K_lds, r32, hi, S.qr, ACT(0));
;     if constexpr (F32) { if (NT > 1) { VMW(); SWRITE_KF(1); SBAR(); SLOAD_F((const float*)Vh, KBASE(1)); } }
;     MASKT(pA0, pA1, 0); partialSM(pA0, pA1, m_reg, mnA, alA);
;     if (NT > 1) { VMW(); if constexpr (F32) { SWRITE_VF(1); SBAR(); if (NT > 2) SLOAD_F((const float*)Kh, KBASE(2)); } else SWRITE_H(1); }
;     __syncthreads();
.Lh1_back:
	v_fmamk_f32 v228, v86, 0x3e0293ee, v253
	v_fmamk_f32 v229, v87, 0x3e0293ee, v253
	s_waitcnt lgkmcnt(6)
	v_mfma_f32_32x32x16_bf16 v[50:65], v[66:69], v[118:121], v[50:65]
	ds_read_b64_tr_b16 v[118:119], v202 offset:0x1400
	ds_read_b64_tr_b16 v[120:121], v202 offset:0x1c00
	v_fmamk_f32 v230, v88, 0x3e0293ee, v253
	v_fmamk_f32 v231, v89, 0x3e0293ee, v253
	v_fmamk_f32 v232, v90, 0x3e0293ee, v253
	s_waitcnt lgkmcnt(6)
	v_mfma_f32_32x32x16_bf16 v[50:65], v[106:109], v[122:125], v[50:65]
	ds_read_b64_tr_b16 v[122:123], v202 offset:0x2400
	ds_read_b64_tr_b16 v[124:125], v202 offset:0x2c00
	v_fmamk_f32 v233, v91, 0x3e0293ee, v253
	v_fmamk_f32 v234, v92, 0x3e0293ee, v253
	v_fmamk_f32 v235, v93, 0x3e0293ee, v253
	s_waitcnt lgkmcnt(6)
	v_mfma_f32_32x32x16_bf16 v[50:65], v[110:113], v[126:129], v[50:65]
	ds_read_b64_tr_b16 v[126:127], v202 offset:0x3400
	ds_read_b64_tr_b16 v[128:129], v202 offset:0x3c00
	v_fmamk_f32 v236, v94, 0x3e0293ee, v253
	v_fmamk_f32 v237, v95, 0x3e0293ee, v253
	v_fmamk_f32 v238, v96, 0x3e0293ee, v253
	s_waitcnt lgkmcnt(6)
	v_mfma_f32_32x32x16_bf16 v[18:33], v[102:105], v[114:117], v[18:33]
	ds_read_b64_tr_b16 v[114:115], v202 offset:0x600
	ds_read_b64_tr_b16 v[116:117], v202 offset:0xe00
	v_fmamk_f32 v239, v97, 0x3e0293ee, v253
	v_fmamk_f32 v98, v98, 0x3e0293ee, v253
	v_fmamk_f32 v99, v99, 0x3e0293ee, v253
	s_waitcnt lgkmcnt(6)
	v_mfma_f32_32x32x16_bf16 v[18:33], v[66:69], v[118:121], v[18:33]
	ds_read_b64_tr_b16 v[118:119], v202 offset:0x1600
	ds_read_b64_tr_b16 v[120:121], v202 offset:0x1e00
	v_fmamk_f32 v100, v100, 0x3e0293ee, v253
	v_fmamk_f32 v101, v101, 0x3e0293ee, v253
	v_fmamk_f32 v86, v70, 0x3e0293ee, v253
	s_waitcnt lgkmcnt(6)
	v_mfma_f32_32x32x16_bf16 v[18:33], v[106:109], v[122:125], v[18:33]
	ds_read_b64_tr_b16 v[122:123], v202 offset:0x2600
	ds_read_b64_tr_b16 v[124:125], v202 offset:0x2e00
	v_fmamk_f32 v95, v71, 0x3e0293ee, v253
	v_fmamk_f32 v96, v72, 0x3e0293ee, v253
	v_fmamk_f32 v97, v73, 0x3e0293ee, v253
	s_waitcnt lgkmcnt(6)
	v_mfma_f32_32x32x16_bf16 v[18:33], v[110:113], v[126:129], v[18:33]
	ds_read_b64_tr_b16 v[126:127], v202 offset:0x3600
	ds_read_b64_tr_b16 v[128:129], v202 offset:0x3e00
	v_fmamk_f32 v179, v74, 0x3e0293ee, v253
	v_fmamk_f32 v87, v75, 0x3e0293ee, v253
	v_fmamk_f32 v88, v76, 0x3e0293ee, v253
	s_waitcnt lgkmcnt(6)
	v_mfma_f32_32x32x16_bf16 v[2:17], v[102:105], v[114:117], v[2:17]
	v_fmamk_f32 v89, v77, 0x3e0293ee, v253
	v_fmamk_f32 v90, v78, 0x3e0293ee, v253
	v_fmamk_f32 v91, v79, 0x3e0293ee, v253
	s_waitcnt lgkmcnt(4)
	v_mfma_f32_32x32x16_bf16 v[2:17], v[66:69], v[118:121], v[2:17]
	v_fmamk_f32 v92, v80, 0x3e0293ee, v253
	v_fmamk_f32 v93, v81, 0x3e0293ee, v253
	v_fmamk_f32 v94, v82, 0x3e0293ee, v253
	s_waitcnt lgkmcnt(2)
	v_mfma_f32_32x32x16_bf16 v[2:17], v[106:109], v[122:125], v[2:17]
	v_fmamk_f32 v180, v83, 0x3e0293ee, v253
	v_fmamk_f32 v181, v84, 0x3e0293ee, v253
	v_fmamk_f32 v178, v85, 0x3e0293ee, v253
	s_waitcnt lgkmcnt(0)
	v_mfma_f32_32x32x16_bf16 v[2:17], v[110:113], v[126:129], v[2:17]
	s_barrier
	s_waitcnt vmcnt(0)
	ds_write_b128 v209, v[162:165]
	ds_write_b128 v210, v[166:169]
	ds_write_b128 v217, v[170:173] offset:32768
	ds_write_b128 v217, v[174:177] offset:40960
	s_and_b64 vcc, exec, s[4:5]
	s_cbranch_vccnz .Lh1_noresc
	s_and_saveexec_b64 s[52:53], s[0:1]
	ds_write_b32 v219, v225 offset:128
	s_or_b64 exec, exec, s[52:53]
	s_waitcnt lgkmcnt(0)
	ds_read_b128 v[102:105], v218 offset:224
	ds_read_b128 v[106:109], v218 offset:192
	ds_read_b128 v[110:113], v218 offset:160
	ds_read_b128 v[114:117], v218 offset:128
	s_waitcnt lgkmcnt(3)
	v_pk_mul_f32 v[48:49], v[48:49], v[104:105]
	s_waitcnt lgkmcnt(2)
	v_pk_mul_f32 v[44:45], v[44:45], v[108:109]
	s_waitcnt lgkmcnt(1)
	v_pk_mul_f32 v[40:41], v[40:41], v[112:113]
	s_waitcnt lgkmcnt(0)
	v_pk_mul_f32 v[36:37], v[36:37], v[116:117]
	v_pk_mul_f32 v[46:47], v[46:47], v[102:103]
	v_pk_mul_f32 v[42:43], v[42:43], v[106:107]
	v_pk_mul_f32 v[38:39], v[38:39], v[110:111]
	v_pk_mul_f32 v[34:35], v[34:35], v[114:115]
	v_pk_mul_f32 v[64:65], v[64:65], v[104:105]
	v_pk_mul_f32 v[60:61], v[60:61], v[108:109]
	v_pk_mul_f32 v[56:57], v[56:57], v[112:113]
	v_pk_mul_f32 v[52:53], v[52:53], v[116:117]
	v_pk_mul_f32 v[62:63], v[62:63], v[102:103]
	v_pk_mul_f32 v[58:59], v[58:59], v[106:107]
	v_pk_mul_f32 v[54:55], v[54:55], v[110:111]
	v_pk_mul_f32 v[50:51], v[50:51], v[114:115]
	v_pk_mul_f32 v[32:33], v[32:33], v[104:105]
	v_pk_mul_f32 v[28:29], v[28:29], v[108:109]
	v_pk_mul_f32 v[24:25], v[24:25], v[112:113]
	v_pk_mul_f32 v[20:21], v[20:21], v[116:117]
	v_pk_mul_f32 v[30:31], v[30:31], v[102:103]
	v_pk_mul_f32 v[26:27], v[26:27], v[106:107]
	v_pk_mul_f32 v[22:23], v[22:23], v[110:111]
	v_pk_mul_f32 v[18:19], v[18:19], v[114:115]
	v_pk_mul_f32 v[16:17], v[16:17], v[104:105]
	v_pk_mul_f32 v[12:13], v[12:13], v[108:109]
	v_pk_mul_f32 v[8:9], v[8:9], v[112:113]
	v_pk_mul_f32 v[4:5], v[4:5], v[116:117]
	v_pk_mul_f32 v[14:15], v[14:15], v[102:103]
	v_pk_mul_f32 v[10:11], v[10:11], v[106:107]
	v_pk_mul_f32 v[6:7], v[6:7], v[110:111]
	v_pk_mul_f32 v[2:3], v[2:3], v[114:115]
; __device__ __forceinline__ void partialSM(f32x16& p0, f32x16& p1, float& m_reg, float& mn, float& alpha) {
;     ...
;     for (int r = 0; r < 16; ++r) p0[r] = __builtin_amdgcn_exp2f(p0[r]);
; }
; __device__ __forceinline__ void finishSM(f32x16& p0, f32x16& p1, float alpha, float& l_reg, bf16x8& pa0, bf16x8& pa1, bf16x8& pa2, bf16x8& pa3) {
;     for (int r = 0; r < 16; ++r) p1[r] = __builtin_amdgcn_exp2f(p1[r]);
;     float ps = 0; for (int r = 0; r < 16; ++r) ps += p0[r]; for (int r = 0; r < 16; ++r) ps += p1[r];
;     { auto rr = __builtin_amdgcn_permlane32_swap(__float_as_uint(ps), __float_as_uint(ps), false, false);
;       ps = __uint_as_float(rr[0]) + __uint_as_float(rr[1]); }
;     l_reg = l_reg * alpha + ps;
;     ...
;     PK4(p0, 0, pa0); PK4(p0, 8, pa1); PK4(p1, 0, pa2); PK4(p1, 8, pa3);
;     ...
; }
; template <int KB, bool SK>
; __device__ __forceinline__ void qkt(f32x16& p0, f32x16& p1, const char* K_lds, int r32, int hi, const bf16x8* qr, bool act) {
;     if (SK && !act) { const float NEG = -__builtin_inff();
; #pragma unroll
;         for (int r = 0; r < 16; ++r) { p0[r] = NEG; p1[r] = NEG; } return; }
;     p0 = f32x16{}; p1 = f32x16{};
;     const char* kb[4];
; #pragma unroll
;     for (int dd = 0; dd < 4; ++dd) kb[dd] = K_lds + KB * SHM_K + KSWZ(r32, (dd * 16 + hi * 8) * 2);
; #pragma unroll
;     for (int d0 = 0; d0 < 8; ++d0) { const char* a = kb[d0 & 3] + (d0 >> 2) * 128;
;         bf16x8 b0 = *reinterpret_cast<const bf16x8*>(a);
;         bf16x8 b1 = *reinterpret_cast<const bf16x8*>(a + 32 * 256);
;         const bf16x8 qf = qr[d0];
;         p0 = __builtin_amdgcn_mfma_f32_32x32x16_bf16(b0, qf, p0, 0, 0, 0);
;         p1 = __builtin_amdgcn_mfma_f32_32x32x16_bf16(b1, qf, p1, 0, 0, 0); }
; }
.Lh1_noresc:
	v_exp_f32_e32 v66, v228
	v_exp_f32_e32 v67, v229
	v_exp_f32_e32 v68, v230
	v_exp_f32_e32 v69, v231
	v_exp_f32_e32 v70, v232
	v_exp_f32_e32 v71, v233
	v_exp_f32_e32 v72, v234
	v_exp_f32_e32 v73, v235
	v_exp_f32_e32 v74, v236
	v_exp_f32_e32 v75, v237
	v_exp_f32_e32 v76, v238
	v_exp_f32_e32 v77, v239
	v_exp_f32_e32 v78, v98
	v_exp_f32_e32 v79, v99
	v_exp_f32_e32 v80, v100
	v_exp_f32_e32 v81, v101
	s_waitcnt lgkmcnt(0)
	s_barrier
	ds_read_b128 v[162:165], v211 offset:32768
	ds_read_b128 v[166:169], v211 offset:40960
	ds_read_b128 v[170:173], v212 offset:32768
	ds_read_b128 v[174:177], v212 offset:40960
	ds_read_b128 v[230:233], v213 offset:32768
	ds_read_b128 v[234:237], v213 offset:40960
	ds_read_b128 v[238:241], v214 offset:32768
	ds_read_b128 v[242:245], v214 offset:40960
	v_exp_f32_e32 v82, v86
	v_exp_f32_e32 v83, v95
	v_exp_f32_e32 v84, v96
	v_exp_f32_e32 v85, v97
	v_exp_f32_e32 v86, v179
	v_exp_f32_e32 v87, v87
	v_exp_f32_e32 v88, v88
	v_exp_f32_e32 v89, v89
	v_exp_f32_e32 v90, v90
	v_exp_f32_e32 v91, v91
	v_exp_f32_e32 v92, v92
	v_exp_f32_e32 v93, v93
	v_exp_f32_e32 v94, v94
	v_exp_f32_e32 v95, v180
	v_exp_f32_e32 v96, v181
	v_exp_f32_e32 v97, v178
	s_waitcnt lgkmcnt(7)
	v_mfma_f32_32x32x16_bf16 v[114:129], v[162:165], v[158:161], 0
	ds_read_b128 v[162:165], v211 offset:32896
	v_add_f32_e32 v178, 0, v66
	v_add_f32_e32 v178, v67, v178
	v_add_f32_e32 v178, v68, v178
	v_add_f32_e32 v178, v69, v178
	s_waitcnt lgkmcnt(7)
	v_mfma_f32_32x32x16_bf16 v[98:113], v[166:169], v[158:161], 0
	ds_read_b128 v[166:169], v211 offset:41088
	v_add_f32_e32 v178, v70, v178
	v_add_f32_e32 v178, v71, v178
	v_add_f32_e32 v178, v72, v178
	v_add_f32_e32 v178, v73, v178
	s_waitcnt lgkmcnt(7)
	v_mfma_f32_32x32x16_bf16 v[114:129], v[170:173], v[154:157], v[114:129]
	ds_read_b128 v[170:173], v212 offset:32896
	v_add_f32_e32 v178, v74, v178
	v_add_f32_e32 v178, v75, v178
	v_add_f32_e32 v178, v76, v178
	v_add_f32_e32 v178, v77, v178
	s_waitcnt lgkmcnt(7)
	v_mfma_f32_32x32x16_bf16 v[98:113], v[174:177], v[154:157], v[98:113]
	ds_read_b128 v[174:177], v212 offset:41088
	v_add_f32_e32 v178, v78, v178
	v_add_f32_e32 v178, v79, v178
	v_add_f32_e32 v178, v80, v178
	v_add_f32_e32 v178, v81, v178
	s_waitcnt lgkmcnt(7)
	v_mfma_f32_32x32x16_bf16 v[114:129], v[230:233], v[150:153], v[114:129]
	ds_read_b128 v[230:233], v213 offset:32896
	v_add_f32_e32 v178, v82, v178
	v_add_f32_e32 v178, v83, v178
	v_add_f32_e32 v178, v84, v178
	v_add_f32_e32 v178, v85, v178
	s_waitcnt lgkmcnt(7)
	v_mfma_f32_32x32x16_bf16 v[98:113], v[234:237], v[150:153], v[98:113]
	ds_read_b128 v[234:237], v213 offset:41088
	v_add_f32_e32 v178, v86, v178
	v_add_f32_e32 v178, v87, v178
	v_add_f32_e32 v178, v88, v178
	v_add_f32_e32 v178, v89, v178
	s_waitcnt lgkmcnt(7)
	v_mfma_f32_32x32x16_bf16 v[114:129], v[238:241], v[134:137], v[114:129]
	ds_read_b128 v[238:241], v214 offset:32896
	v_add_f32_e32 v178, v90, v178
	v_add_f32_e32 v178, v91, v178
	v_add_f32_e32 v178, v92, v178
	v_add_f32_e32 v178, v93, v178
	s_waitcnt lgkmcnt(7)
	v_mfma_f32_32x32x16_bf16 v[98:113], v[242:245], v[134:137], v[98:113]
	ds_read_b128 v[242:245], v214 offset:41088
	v_add_f32_e32 v178, v94, v178
	v_add_f32_e32 v178, v95, v178
	v_add_f32_e32 v178, v96, v178
	v_add_f32_e32 v228, v97, v178
	s_waitcnt lgkmcnt(7)
	v_mfma_f32_32x32x16_bf16 v[114:129], v[162:165], v[138:141], v[114:129]
	v_mov_b32_e32 v229, v228
	s_nop 1
	v_permlane32_swap_b32_e32 v228, v229
	v_cvt_pk_bf16_f32 v178, v66, v67
	v_cvt_pk_bf16_f32 v179, v68, v69
	s_waitcnt lgkmcnt(6)
	v_mfma_f32_32x32x16_bf16 v[98:113], v[166:169], v[138:141], v[98:113]
	v_cvt_pk_bf16_f32 v180, v70, v71
	v_cvt_pk_bf16_f32 v181, v72, v73
	v_cvt_pk_bf16_f32 v182, v74, v75
	v_cvt_pk_bf16_f32 v183, v76, v77
	s_waitcnt lgkmcnt(5)
	v_mfma_f32_32x32x16_bf16 v[114:129], v[170:173], v[142:145], v[114:129]
	v_cvt_pk_bf16_f32 v184, v78, v79
	v_cvt_pk_bf16_f32 v185, v80, v81
	v_cvt_pk_bf16_f32 v186, v82, v83
	s_waitcnt lgkmcnt(4)
	v_mfma_f32_32x32x16_bf16 v[98:113], v[174:177], v[142:145], v[98:113]
	v_cvt_pk_bf16_f32 v187, v84, v85
	v_cvt_pk_bf16_f32 v188, v86, v87
	v_cvt_pk_bf16_f32 v189, v88, v89
	s_waitcnt lgkmcnt(3)
	v_mfma_f32_32x32x16_bf16 v[114:129], v[230:233], v[146:149], v[114:129]
	v_cvt_pk_bf16_f32 v190, v90, v91
	v_cvt_pk_bf16_f32 v191, v92, v93
	v_cvt_pk_bf16_f32 v192, v94, v95
	s_waitcnt lgkmcnt(2)
	v_mfma_f32_32x32x16_bf16 v[98:113], v[234:237], v[146:149], v[98:113]
	v_cvt_pk_bf16_f32 v193, v96, v97
	s_nop 1
	v_permlane32_swap_b32_e32 v178, v180
	v_permlane32_swap_b32_e32 v179, v181
	s_waitcnt lgkmcnt(1)
	v_mfma_f32_32x32x16_bf16 v[114:129], v[238:241], v[130:133], v[114:129]
	v_permlane32_swap_b32_e32 v182, v184
	v_permlane32_swap_b32_e32 v183, v185
	v_permlane32_swap_b32_e32 v186, v188
	s_waitcnt lgkmcnt(0)
	v_mfma_f32_32x32x16_bf16 v[98:113], v[242:245], v[130:133], v[98:113]
	v_permlane32_swap_b32_e32 v187, v189
	v_permlane32_swap_b32_e32 v190, v192
	v_permlane32_swap_b32_e32 v191, v193
	s_add_i32 s4, s25, 1
	s_cmp_le_u32 s4, s24
	s_cselect_b64 s[76:77], -1, 0
	s_cmp_gt_u32 s4, s24
	s_cbranch_scc1 .LBB0_1137
	v_add_u32_e32 v84, 0x4000, v255
	v_add_u32_e32 v85, 0x6000, v255
	global_load_dwordx4 v[162:165], v84, s[42:43]
	global_load_dwordx4 v[166:169], v85, s[42:43]
	global_load_dwordx4 v[170:173], v84, s[22:23]
	global_load_dwordx4 v[174:177], v85, s[22:23]
; __device__ __forceinline__ void mask_tile(f32x16& p0, f32x16& p1, int dq, unsigned W) {
;     const float NEG = -__builtin_inff();
; #pragma unroll
;     for (int r = 0; r < 16; ++r) {
;         const int c = (r & 3) + 8 * (r >> 2);
;         if ((unsigned)(dq - c) >= W) p0[r] = NEG;
;         if ((unsigned)(dq - c - 32) >= W) p1[r] = NEG;
;     }
; }
; __device__ __forceinline__ void partialSM(f32x16& p0, f32x16& p1, float& m_reg, float& mn, float& alpha) {
;     float pmax = p0[0]; for (int r = 1; r < 16; ++r) pmax = fmaxf(pmax, p0[r]); for (int r = 0; r < 16; ++r) pmax = fmaxf(pmax, p1[r]);
;     { auto rr = __builtin_amdgcn_permlane32_swap(__float_as_uint(pmax), __float_as_uint(pmax), false, false);
;       pmax = fmaxf(__uint_as_float(rr[0]), __uint_as_float(rr[1])); }
;     constexpr float C2 = 1.4426950408889634f * SCALE;
;     if (__builtin_expect(__all((pmax - m_reg) * SCALE <= THR), 1)) { mn = m_reg; alpha = 1.f; }
;     else { mn = fmaxf(m_reg, pmax); alpha = __builtin_amdgcn_exp2f((m_reg - mn) * C2); m_reg = mn; }
;     const float mnL = -mn * C2;
;     for (int r = 0; r < 16; ++r) p0[r] = fmaf(p0[r], C2, mnL); for (int r = 0; r < 16; ++r) p1[r] = fmaf(p1[r], C2, mnL);
;     for (int r = 0; r < 16; ++r) p0[r] = __builtin_amdgcn_exp2f(p0[r]);
; }
; template <int VB, bool SK>
; __device__ __forceinline__ void pv_tile(f32x16* o, int vb0, bf16x8 pa0, bf16x8 pa1, bf16x8 pa2, bf16x8 pa3, bool act) {
;     if (SK && !act) return;
;     ...
;     PV_D0(0); PV_D0(1); PV_D0(2); PV_D0(3);
.LBB0_1137:
	s_sub_i32 s27, s26, 63
	s_cmp_le_i32 s26, s13
	s_cselect_b64 s[4:5], -1, 0
	s_cmp_gt_i32 s27, s15
	s_cselect_b64 s[52:53], -1, 0
	s_and_b64 s[4:5], s[4:5], s[52:53]
	s_and_b64 vcc, exec, s[4:5]
	ds_read_b64_tr_b16 v[230:231], v202 offset:0x4000
	ds_read_b64_tr_b16 v[232:233], v202 offset:0x4800
	ds_read_b64_tr_b16 v[234:235], v202 offset:0x5000
	ds_read_b64_tr_b16 v[236:237], v202 offset:0x5800
	ds_read_b64_tr_b16 v[238:239], v202 offset:0x6000
	ds_read_b64_tr_b16 v[240:241], v202 offset:0x6800
	ds_read_b64_tr_b16 v[242:243], v202 offset:0x7000
	ds_read_b64_tr_b16 v[244:245], v202 offset:0x7800
	s_cbranch_vccnz .Lh2_nomask
	v_add_u32_e32 v226, s80, v222
	v_add_u32_e32 v66, 0xffffff80, v226
	v_cmp_gt_u32_e32 vcc, s85, v66
	v_add_u32_e32 v66, 0xffffff60, v226
	s_nop 0
	v_cndmask_b32_e32 v114, v215, v114, vcc
	v_cmp_gt_u32_e32 vcc, s85, v66
	v_add_u32_e32 v66, 0xffffff7f, v226
	s_nop 0
	v_cndmask_b32_e32 v98, v215, v98, vcc
	v_cmp_gt_u32_e32 vcc, s85, v66
	v_add_u32_e32 v66, 0xffffff5f, v226
	s_nop 0
	v_cndmask_b32_e32 v115, v215, v115, vcc
	v_cmp_gt_u32_e32 vcc, s85, v66
	v_add_u32_e32 v66, 0xffffff7e, v226
	s_nop 0
	v_cndmask_b32_e32 v99, v215, v99, vcc
	v_cmp_gt_u32_e32 vcc, s85, v66
	v_add_u32_e32 v66, 0xffffff5e, v226
	s_nop 0
	v_cndmask_b32_e32 v116, v215, v116, vcc
	v_cmp_gt_u32_e32 vcc, s85, v66
	v_add_u32_e32 v66, 0xffffff7d, v226
	s_nop 0
	v_cndmask_b32_e32 v100, v215, v100, vcc
	v_cmp_gt_u32_e32 vcc, s85, v66
	v_add_u32_e32 v66, 0xffffff5d, v226
	s_nop 0
	v_cndmask_b32_e32 v117, v215, v117, vcc
	v_cmp_gt_u32_e32 vcc, s85, v66
	v_add_u32_e32 v66, 0xffffff78, v226
	s_nop 0
	v_cndmask_b32_e32 v101, v215, v101, vcc
	v_cmp_gt_u32_e32 vcc, s85, v66
	v_add_u32_e32 v66, 0xffffff58, v226
	s_nop 0
	v_cndmask_b32_e32 v118, v215, v118, vcc
	v_cmp_gt_u32_e32 vcc, s85, v66
	v_add_u32_e32 v66, 0xffffff77, v226
	s_nop 0
	v_cndmask_b32_e32 v102, v215, v102, vcc
	v_cmp_gt_u32_e32 vcc, s85, v66
	v_add_u32_e32 v66, 0xffffff57, v226
	s_nop 0
	v_cndmask_b32_e32 v119, v215, v119, vcc
	v_cmp_gt_u32_e32 vcc, s85, v66
	v_add_u32_e32 v66, 0xffffff76, v226
	s_nop 0
	v_cndmask_b32_e32 v103, v215, v103, vcc
	v_cmp_gt_u32_e32 vcc, s85, v66
	v_add_u32_e32 v66, 0xffffff56, v226
	s_nop 0
	v_cndmask_b32_e32 v120, v215, v120, vcc
	v_cmp_gt_u32_e32 vcc, s85, v66
	v_add_u32_e32 v66, 0xffffff75, v226
	s_nop 0
	v_cndmask_b32_e32 v104, v215, v104, vcc
	v_cmp_gt_u32_e32 vcc, s85, v66
	v_add_u32_e32 v66, 0xffffff55, v226
	s_nop 0
	v_cndmask_b32_e32 v121, v215, v121, vcc
	v_cmp_gt_u32_e32 vcc, s85, v66
	v_add_u32_e32 v66, 0xffffff70, v226
	s_nop 0
	v_cndmask_b32_e32 v105, v215, v105, vcc
	v_cmp_gt_u32_e32 vcc, s85, v66
	v_add_u32_e32 v66, 0xffffff50, v226
	s_nop 0
	v_cndmask_b32_e32 v122, v215, v122, vcc
	v_cmp_gt_u32_e32 vcc, s85, v66
	v_add_u32_e32 v66, 0xffffff6f, v226
	s_nop 0
	v_cndmask_b32_e32 v106, v215, v106, vcc
	v_cmp_gt_u32_e32 vcc, s85, v66
	v_add_u32_e32 v66, 0xffffff4f, v226
	s_nop 0
	v_cndmask_b32_e32 v123, v215, v123, vcc
	v_cmp_gt_u32_e32 vcc, s85, v66
	v_add_u32_e32 v66, 0xffffff6e, v226
	s_nop 0
	v_cndmask_b32_e32 v107, v215, v107, vcc
	v_cmp_gt_u32_e32 vcc, s85, v66
	v_add_u32_e32 v66, 0xffffff4e, v226
	s_nop 0
	v_cndmask_b32_e32 v124, v215, v124, vcc
	v_cmp_gt_u32_e32 vcc, s85, v66
	v_add_u32_e32 v66, 0xffffff6d, v226
	s_nop 0
	v_cndmask_b32_e32 v108, v215, v108, vcc
	v_cmp_gt_u32_e32 vcc, s85, v66
	v_add_u32_e32 v66, 0xffffff4d, v226
	s_nop 0
	v_cndmask_b32_e32 v125, v215, v125, vcc
	v_cmp_gt_u32_e32 vcc, s85, v66
	v_add_u32_e32 v66, 0xffffff68, v226
	s_nop 0
	v_cndmask_b32_e32 v109, v215, v109, vcc
	v_cmp_gt_u32_e32 vcc, s85, v66
	v_add_u32_e32 v66, 0xffffff48, v226
	s_nop 0
	v_cndmask_b32_e32 v126, v215, v126, vcc
	v_cmp_gt_u32_e32 vcc, s85, v66
	v_add_u32_e32 v66, 0xffffff67, v226
	s_nop 0
	v_cndmask_b32_e32 v110, v215, v110, vcc
	v_cmp_gt_u32_e32 vcc, s85, v66
	v_add_u32_e32 v66, 0xffffff47, v226
	s_nop 0
	v_cndmask_b32_e32 v127, v215, v127, vcc
	v_cmp_gt_u32_e32 vcc, s85, v66
	v_add_u32_e32 v66, 0xffffff66, v226
	s_nop 0
	v_cndmask_b32_e32 v111, v215, v111, vcc
	v_cmp_gt_u32_e32 vcc, s85, v66
	v_add_u32_e32 v66, 0xffffff46, v226
	s_nop 0
	v_cndmask_b32_e32 v128, v215, v128, vcc
	v_cmp_gt_u32_e32 vcc, s85, v66
	v_add_u32_e32 v66, 0xffffff65, v226
	s_nop 0
	v_cndmask_b32_e32 v112, v215, v112, vcc
	v_cmp_gt_u32_e32 vcc, s85, v66
	v_add_u32_e32 v66, 0xffffff45, v226
	s_nop 0
	v_cndmask_b32_e32 v129, v215, v129, vcc
	v_cmp_gt_u32_e32 vcc, s85, v66
	s_nop 1
	v_cndmask_b32_e32 v113, v215, v113, vcc
.Lh2_nomask:
	v_max_f32_e32 v66, v114, v115
	v_max3_f32 v66, v66, v116, v117
	v_max3_f32 v66, v66, v118, v119
	v_max3_f32 v66, v66, v120, v121
	v_max3_f32 v66, v66, v122, v123
	s_waitcnt lgkmcnt(6)
	v_mfma_f32_32x32x16_bf16 v[34:49], v[178:181], v[230:233], v[34:49]
	ds_read_b64_tr_b16 v[230:231], v202 offset:0x4200
	ds_read_b64_tr_b16 v[232:233], v202 offset:0x4a00
	v_max3_f32 v66, v66, v124, v125
	v_max3_f32 v66, v66, v126, v127
	v_max3_f32 v66, v66, v128, v129
	v_max3_f32 v66, v66, v98, v99
	s_waitcnt lgkmcnt(6)
	v_mfma_f32_32x32x16_bf16 v[34:49], v[182:185], v[234:237], v[34:49]
	ds_read_b64_tr_b16 v[234:235], v202 offset:0x5200
	ds_read_b64_tr_b16 v[236:237], v202 offset:0x5a00
	v_max3_f32 v66, v66, v100, v101
	v_max3_f32 v66, v66, v102, v103
	v_max3_f32 v66, v66, v104, v105
	v_max3_f32 v66, v66, v106, v107
	s_waitcnt lgkmcnt(6)
	v_mfma_f32_32x32x16_bf16 v[34:49], v[186:189], v[238:241], v[34:49]
	ds_read_b64_tr_b16 v[238:239], v202 offset:0x6200
	ds_read_b64_tr_b16 v[240:241], v202 offset:0x6a00
	v_max3_f32 v66, v66, v108, v109
	v_max3_f32 v66, v66, v110, v111
	v_max3_f32 v66, v66, v112, v113
	v_mov_b32_e32 v67, v66
	s_waitcnt lgkmcnt(6)
	v_mfma_f32_32x32x16_bf16 v[34:49], v[190:193], v[242:245], v[34:49]
	ds_read_b64_tr_b16 v[242:243], v202 offset:0x7200
	ds_read_b64_tr_b16 v[244:245], v202 offset:0x7a00
	s_nop 1
	v_permlane32_swap_b32_e32 v66, v67
	v_max_f32_e32 v66, v66, v67
	v_sub_f32_e32 v67, v66, v252
	v_mul_f32_e32 v67, 0x3db504f3, v67
	s_waitcnt lgkmcnt(6)
	v_mfma_f32_32x32x16_bf16 v[50:65], v[178:181], v[230:233], v[50:65]
	ds_read_b64_tr_b16 v[230:231], v202 offset:0x4400
	ds_read_b64_tr_b16 v[232:233], v202 offset:0x4c00
	v_cmp_ge_f32_e32 vcc, s86, v67
	s_cmp_eq_u64 vcc, exec
	s_cselect_b64 s[4:5], -1, 0
	v_mov_b32_e32 v254, 1.0
	s_cbranch_scc0 .Lh2_rare
; __device__ __forceinline__ void partialSM(f32x16& p0, f32x16& p1, float& m_reg, float& mn, float& alpha) {
;     float pmax = p0[0]; for (int r = 1; r < 16; ++r) pmax = fmaxf(pmax, p0[r]); for (int r = 0; r < 16; ++r) pmax = fmaxf(pmax, p1[r]);
;     { auto rr = __builtin_amdgcn_permlane32_swap(__float_as_uint(pmax), __float_as_uint(pmax), false, false);
;       pmax = fmaxf(__uint_as_float(rr[0]), __uint_as_float(rr[1])); }
;     constexpr float C2 = 1.4426950408889634f * SCALE;
;     if (__builtin_expect(__all((pmax - m_reg) * SCALE <= THR), 1)) { mn = m_reg; alpha = 1.f; }
;     else { mn = fmaxf(m_reg, pmax); alpha = __builtin_amdgcn_exp2f((m_reg - mn) * C2); m_reg = mn; }
;     const float mnL = -mn * C2;
;     for (int r = 0; r < 16; ++r) p0[r] = fmaf(p0[r], C2, mnL); for (int r = 0; r < 16; ++r) p1[r] = fmaf(p1[r], C2, mnL);
;     for (int r = 0; r < 16; ++r) p0[r] = __builtin_amdgcn_exp2f(p0[r]);
; }
; template <class TIn, class TOut>
; __device__ __forceinline__ void causal_swa_block(const BlockRef<TIn, TOut>& cur, const BlockRef<TIn, TOut>& nxt, int skv, int W, char* lds, Seam<TIn>& S) {
;     ...
;     for (int t = 1; t + 1 < NT; t += 2) {
;         HALF_STEP(pB0, pB1, mnB, alB, pA0, pA1, alA, t, 1, 0, 0);
;         HALF_STEP(pA0, pA1, mnA, alA, pB0, pB1, alB, t + 1, 0, 1, 1);
;     }
.Lh2_back:
	v_fmamk_f32 v68, v114, 0x3e0293ee, v253
	v_fmamk_f32 v69, v115, 0x3e0293ee, v253
	s_waitcnt lgkmcnt(6)
	v_mfma_f32_32x32x16_bf16 v[50:65], v[182:185], v[234:237], v[50:65]
	ds_read_b64_tr_b16 v[234:235], v202 offset:0x5400
	ds_read_b64_tr_b16 v[236:237], v202 offset:0x5c00
	v_fmamk_f32 v70, v116, 0x3e0293ee, v253
	v_fmamk_f32 v71, v117, 0x3e0293ee, v253
	v_fmamk_f32 v79, v118, 0x3e0293ee, v253
	v_fmamk_f32 v80, v119, 0x3e0293ee, v253
	s_waitcnt lgkmcnt(6)
	v_mfma_f32_32x32x16_bf16 v[50:65], v[186:189], v[238:241], v[50:65]
	ds_read_b64_tr_b16 v[238:239], v202 offset:0x6400
	ds_read_b64_tr_b16 v[240:241], v202 offset:0x6c00
	v_fmamk_f32 v72, v120, 0x3e0293ee, v253
	v_fmamk_f32 v73, v121, 0x3e0293ee, v253
	v_fmamk_f32 v81, v122, 0x3e0293ee, v253
	v_fmamk_f32 v82, v123, 0x3e0293ee, v253
	s_waitcnt lgkmcnt(6)
	v_mfma_f32_32x32x16_bf16 v[50:65], v[190:193], v[242:245], v[50:65]
	ds_read_b64_tr_b16 v[242:243], v202 offset:0x7400
	ds_read_b64_tr_b16 v[244:245], v202 offset:0x7c00
	v_fmamk_f32 v74, v124, 0x3e0293ee, v253
	v_fmamk_f32 v75, v125, 0x3e0293ee, v253
	v_fmamk_f32 v76, v126, 0x3e0293ee, v253
	v_fmamk_f32 v77, v127, 0x3e0293ee, v253
	s_waitcnt lgkmcnt(6)
	v_mfma_f32_32x32x16_bf16 v[18:33], v[178:181], v[230:233], v[18:33]
	ds_read_b64_tr_b16 v[230:231], v202 offset:0x4600
	ds_read_b64_tr_b16 v[232:233], v202 offset:0x4e00
	v_fmamk_f32 v83, v128, 0x3e0293ee, v253
	v_fmamk_f32 v78, v129, 0x3e0293ee, v253
	v_fmamk_f32 v126, v98, 0x3e0293ee, v253
	v_fmamk_f32 v127, v99, 0x3e0293ee, v253
	s_waitcnt lgkmcnt(6)
	v_mfma_f32_32x32x16_bf16 v[18:33], v[182:185], v[234:237], v[18:33]
	ds_read_b64_tr_b16 v[234:235], v202 offset:0x5600
	ds_read_b64_tr_b16 v[236:237], v202 offset:0x5e00
	v_fmamk_f32 v124, v100, 0x3e0293ee, v253
	v_fmamk_f32 v125, v101, 0x3e0293ee, v253
	v_fmamk_f32 v120, v102, 0x3e0293ee, v253
	s_waitcnt lgkmcnt(6)
	v_mfma_f32_32x32x16_bf16 v[18:33], v[186:189], v[238:241], v[18:33]
	ds_read_b64_tr_b16 v[238:239], v202 offset:0x6600
	ds_read_b64_tr_b16 v[240:241], v202 offset:0x6e00
	v_fmamk_f32 v121, v103, 0x3e0293ee, v253
	v_fmamk_f32 v116, v104, 0x3e0293ee, v253
	v_fmamk_f32 v117, v105, 0x3e0293ee, v253
	s_waitcnt lgkmcnt(6)
	v_mfma_f32_32x32x16_bf16 v[18:33], v[190:193], v[242:245], v[18:33]
	ds_read_b64_tr_b16 v[242:243], v202 offset:0x7600
	ds_read_b64_tr_b16 v[244:245], v202 offset:0x7e00
	v_fmamk_f32 v114, v106, 0x3e0293ee, v253
	v_fmamk_f32 v115, v107, 0x3e0293ee, v253
	v_fmamk_f32 v128, v108, 0x3e0293ee, v253
	s_waitcnt lgkmcnt(6)
	v_mfma_f32_32x32x16_bf16 v[2:17], v[178:181], v[230:233], v[2:17]
	v_fmamk_f32 v129, v109, 0x3e0293ee, v253
	v_fmamk_f32 v122, v110, 0x3e0293ee, v253
	v_fmamk_f32 v123, v111, 0x3e0293ee, v253
	s_waitcnt lgkmcnt(4)
	v_mfma_f32_32x32x16_bf16 v[2:17], v[182:185], v[234:237], v[2:17]
	v_fmamk_f32 v118, v112, 0x3e0293ee, v253
	v_fmamk_f32 v119, v113, 0x3e0293ee, v253
	v_add_f32_e32 v98, v223, v224
	s_waitcnt lgkmcnt(2)
	v_mfma_f32_32x32x16_bf16 v[2:17], v[186:189], v[238:241], v[2:17]
	v_fmac_f32_e32 v98, v197, v221
	v_add_f32_e32 v221, v228, v229
	v_fmac_f32_e32 v221, v98, v225
	s_waitcnt lgkmcnt(0)
	v_mfma_f32_32x32x16_bf16 v[2:17], v[190:193], v[242:245], v[2:17]
	s_andn2_b64 vcc, exec, s[76:77]
	s_barrier
	s_cbranch_vccnz .Lh2_nowrite
	s_waitcnt vmcnt(0)
	ds_write_b128 v209, v[162:165] offset:16384
	ds_write_b128 v210, v[166:169] offset:16384
	ds_write_b128 v217, v[170:173] offset:49152
	ds_write_b128 v217, v[174:177] offset:57344
.Lh2_nowrite:
	v_add_u32_e32 v194, 0x4000, v194
	v_add_u32_e32 v222, 0xffffff80, v222
	v_add_u32_e32 v255, 0x8000, v255
	s_addk_i32 s26, 0x80
	s_add_i32 s25, s25, 2
	s_and_b64 vcc, exec, s[4:5]
	s_cbranch_vccnz .Lh2_noresc
	s_and_saveexec_b64 s[52:53], s[0:1]
	ds_write_b32 v219, v254 offset:128
	s_or_b64 exec, exec, s[52:53]
	s_waitcnt lgkmcnt(0)
	ds_read_b128 v[164:167], v218 offset:224
	ds_read_b128 v[168:171], v218 offset:192
	ds_read_b128 v[172:175], v218 offset:160
	ds_read_b128 v[180:183], v218 offset:128
	s_waitcnt lgkmcnt(3)
	v_pk_mul_f32 v[48:49], v[48:49], v[166:167]
	s_waitcnt lgkmcnt(2)
	v_pk_mul_f32 v[44:45], v[44:45], v[170:171]
	s_waitcnt lgkmcnt(1)
	v_pk_mul_f32 v[40:41], v[40:41], v[174:175]
	s_waitcnt lgkmcnt(0)
	v_pk_mul_f32 v[36:37], v[36:37], v[182:183]
	v_pk_mul_f32 v[46:47], v[46:47], v[164:165]
	v_pk_mul_f32 v[42:43], v[42:43], v[168:169]
	v_pk_mul_f32 v[38:39], v[38:39], v[172:173]
	v_pk_mul_f32 v[34:35], v[34:35], v[180:181]
	v_pk_mul_f32 v[64:65], v[64:65], v[166:167]
	v_pk_mul_f32 v[60:61], v[60:61], v[170:171]
	v_pk_mul_f32 v[56:57], v[56:57], v[174:175]
	v_pk_mul_f32 v[52:53], v[52:53], v[182:183]
	v_pk_mul_f32 v[62:63], v[62:63], v[164:165]
	v_pk_mul_f32 v[58:59], v[58:59], v[168:169]
	v_pk_mul_f32 v[54:55], v[54:55], v[172:173]
	v_pk_mul_f32 v[50:51], v[50:51], v[180:181]
	v_pk_mul_f32 v[32:33], v[32:33], v[166:167]
	v_pk_mul_f32 v[28:29], v[28:29], v[170:171]
	v_pk_mul_f32 v[24:25], v[24:25], v[174:175]
	v_pk_mul_f32 v[20:21], v[20:21], v[182:183]
	v_pk_mul_f32 v[30:31], v[30:31], v[164:165]
	v_pk_mul_f32 v[26:27], v[26:27], v[168:169]
	v_pk_mul_f32 v[22:23], v[22:23], v[172:173]
	v_pk_mul_f32 v[18:19], v[18:19], v[180:181]
	v_pk_mul_f32 v[16:17], v[16:17], v[166:167]
	v_pk_mul_f32 v[12:13], v[12:13], v[170:171]
	v_pk_mul_f32 v[8:9], v[8:9], v[174:175]
	v_pk_mul_f32 v[4:5], v[4:5], v[182:183]
	v_pk_mul_f32 v[14:15], v[14:15], v[164:165]
	v_pk_mul_f32 v[10:11], v[10:11], v[168:169]
	v_pk_mul_f32 v[6:7], v[6:7], v[172:173]
	v_pk_mul_f32 v[2:3], v[2:3], v[180:181]
.Lh2_noresc:
	v_exp_f32_e32 v170, v68
	v_exp_f32_e32 v171, v69
	v_exp_f32_e32 v172, v70
	v_exp_f32_e32 v173, v71
	v_exp_f32_e32 v174, v79
	v_exp_f32_e32 v176, v80
	v_exp_f32_e32 v175, v72
	v_exp_f32_e32 v177, v73
	v_exp_f32_e32 v162, v81
	v_exp_f32_e32 v163, v82
	v_exp_f32_e32 v164, v74
	v_exp_f32_e32 v166, v75
	v_exp_f32_e32 v165, v76
	v_exp_f32_e32 v167, v77
	v_exp_f32_e32 v168, v83
	v_exp_f32_e32 v169, v78
	s_cmp_gt_u32 s25, s24
	s_waitcnt lgkmcnt(0)
	s_barrier
	s_cbranch_scc1 .Lattn_exit
	v_mov_b32_e32 v197, v254
	s_branch .LBB0_1129
.Lh1_rare:
	v_max_f32_e32 v242, v252, v240
	v_sub_f32_e32 v241, v252, v242
	v_mul_f32_e32 v241, 0x3e0293ee, v241
	v_exp_f32_e32 v225, v241
	v_mov_b32_e32 v252, v242
	v_mul_f32_e32 v253, 0xbe0293ee, v242
	s_branch .Lh1_back
.Lh2_rare:
	v_max_f32_e32 v84, v252, v66
	v_sub_f32_e32 v85, v252, v84
	v_mul_f32_e32 v85, 0x3e0293ee, v85
	v_exp_f32_e32 v254, v85
	v_mov_b32_e32 v252, v84
	v_mul_f32_e32 v253, 0xbe0293ee, v84
	s_branch .Lh2_back
.Lattn_exit:
	v_mov_b32_e32 v178, v252
	v_mov_b32_e32 v179, v254

; __global__ void __launch_bounds__(NWAVES * 64, 2) mk_fwd(Args args) {
	.amdhsa_kernel _Z6mk_fwd4Args
		.amdhsa_group_segment_fixed_size 0
		.amdhsa_private_segment_fixed_size 0
		.amdhsa_kernarg_size 456
		.amdhsa_user_sgpr_count 2
		.amdhsa_user_sgpr_dispatch_ptr 0
		.amdhsa_user_sgpr_queue_ptr 0
		.amdhsa_user_sgpr_kernarg_segment_ptr 1
		.amdhsa_user_sgpr_dispatch_id 0
		.amdhsa_user_sgpr_kernarg_preload_length 0
		.amdhsa_user_sgpr_kernarg_preload_offset 0
		.amdhsa_user_sgpr_private_segment_size 0
		.amdhsa_uses_dynamic_stack 0
		.amdhsa_enable_private_segment 0
		.amdhsa_system_sgpr_workgroup_id_x 1
		.amdhsa_system_sgpr_workgroup_id_y 0
		.amdhsa_system_sgpr_workgroup_id_z 0
		.amdhsa_system_sgpr_workgroup_info 0
		.amdhsa_system_vgpr_workitem_id 2
		.amdhsa_next_free_vgpr 256
		.amdhsa_next_free_sgpr 98
		.amdhsa_accum_offset 256
		.amdhsa_reserve_vcc 1
		.amdhsa_float_round_mode_32 0
		.amdhsa_float_round_mode_16_64 0
		.amdhsa_float_denorm_mode_32 3
		.amdhsa_float_denorm_mode_16_64 3
		.amdhsa_dx10_clamp 1
		.amdhsa_ieee_mode 1
		.amdhsa_fp16_overflow 0
		.amdhsa_tg_split 0
		.amdhsa_exception_fp_ieee_invalid_op 0
		.amdhsa_exception_fp_denorm_src 0
		.amdhsa_exception_fp_ieee_div_zero 0
		.amdhsa_exception_fp_ieee_overflow 0
		.amdhsa_exception_fp_ieee_underflow 0
		.amdhsa_exception_fp_ieee_inexact 0
		.amdhsa_exception_int_div_zero 0
	.end_amdhsa_kernel

; __global__ void __launch_bounds__(NWAVES * 64, 2) mk_fwd(Args args) {
amdhsa.kernels:
  - .agpr_count:     0
    .args:
      - .offset:         0
        .size:           200
        .value_kind:     by_value
      - .offset:         200
        .size:           4
        .value_kind:     hidden_block_count_x
      - .offset:         204
        .size:           4
        .value_kind:     hidden_block_count_y
      - .offset:         208
        .size:           4
        .value_kind:     hidden_block_count_z
      - .offset:         212
        .size:           2
        .value_kind:     hidden_group_size_x
      - .offset:         214
        .size:           2
        .value_kind:     hidden_group_size_y
      - .offset:         216
        .size:           2
        .value_kind:     hidden_group_size_z
      - .offset:         218
        .size:           2
        .value_kind:     hidden_remainder_x
      - .offset:         220
        .size:           2
        .value_kind:     hidden_remainder_y
      - .offset:         222
        .size:           2
        .value_kind:     hidden_remainder_z
      - .offset:         240
        .size:           8
        .value_kind:     hidden_global_offset_x
      - .offset:         248
        .size:           8
        .value_kind:     hidden_global_offset_y
      - .offset:         256
        .size:           8
        .value_kind:     hidden_global_offset_z
      - .offset:         264
        .size:           2
        .value_kind:     hidden_grid_dims
      - .offset:         288
        .size:           8
        .value_kind:     hidden_multigrid_sync_arg
      - .offset:         320
        .size:           4
        .value_kind:     hidden_dynamic_lds_size
    .group_segment_fixed_size: 0
    .kernarg_segment_align: 8
    .kernarg_segment_size: 456
    .language:       OpenCL C
    .language_version:
      - 2
      - 0
    .max_flat_workgroup_size: 512
    .name:           _Z6mk_fwd4Args
    .private_segment_fixed_size: 0
    .sgpr_count:     104
    .sgpr_spill_count: 28
    .symbol:         _Z6mk_fwd4Args.kd
    .uniform_work_group_size: 1
    .uses_dynamic_stack: false
    .vgpr_count:     256
    .vgpr_spill_count: 0
    .wavefront_size: 64
